# attention LDS tile loop: all eight V-fragment ds_reads of the PV block issued up front into dead registers, counted lgkmcnt waits
# speedup vs baseline: 1.0116x; 1.0097x over previous
; __device__ __forceinline__ void attn_tile_scores(AttnState& st, u32x4 (&pw)[4], const bf16x8 (&qf)[4], const bf16x8 (&kf)[2][4], int kv0, int P0, int pq, int hi) {
;     ...
;     for (int r = 0; r < 16; ++r) { k0v[r] = __builtin_amdgcn_rcpf(1.0f + __builtin_amdgcn_exp2f(s0[r])); k1v[r] = __builtin_amdgcn_rcpf(1.0f + __builtin_amdgcn_exp2f(s1[r])); }
; #pragma unroll
;     for (int r = 0; r < 16; r += 2) { p0 *= k0v[r]; p1 *= k0v[r + 1]; p2 *= k1v[r]; p3 *= k1v[r + 1]; }
;     const float tot = (p0 * p1) * (p2 * p3);
;     const float oth = __shfl_xor(tot, 32);
.LBB0_280:
	s_nop 7
	v_exp_f32_e32 v8, v67
	s_nop 1
	v_exp_f32_e32 v11, v51
	v_exp_f32_e32 v12, v68
	v_exp_f32_e32 v14, v69
	v_add_f32_e32 v8, 1.0, v8
	v_rcp_f32_e32 v9, v8
	v_add_f32_e32 v8, 1.0, v11
	v_exp_f32_e32 v11, v52
	v_add_f32_e32 v12, 1.0, v12
	v_rcp_f32_e32 v13, v12
	v_add_f32_e32 v14, 1.0, v14
	v_add_f32_e32 v11, 1.0, v11
	v_rcp_f32_e32 v12, v11
	v_exp_f32_e32 v11, v53
	v_exp_f32_e32 v2, v64
	v_exp_f32_e32 v3, v48
	v_exp_f32_e32 v4, v65
	v_add_f32_e32 v11, 1.0, v11
	v_rcp_f32_e32 v15, v14
	v_exp_f32_e32 v48, v70
	v_rcp_f32_e32 v14, v11
	v_exp_f32_e32 v11, v54
	v_exp_f32_e32 v6, v49
	v_add_f32_e32 v2, 1.0, v2
	v_add_f32_e32 v5, 1.0, v3
	v_add_f32_e32 v4, 1.0, v4
	v_add_f32_e32 v48, 1.0, v48
	v_add_f32_e32 v11, 1.0, v11
	v_rcp_f32_e32 v3, v2
	v_rcp_f32_e32 v2, v5
	v_rcp_f32_e32 v5, v4
	v_add_f32_e32 v4, 1.0, v6
	v_exp_f32_e32 v6, v50
	v_rcp_f32_e32 v49, v48
	v_exp_f32_e32 v50, v71
	v_rcp_f32_e32 v48, v11
	v_exp_f32_e32 v11, v55
	v_exp_f32_e32 v52, v72
	v_add_f32_e32 v50, 1.0, v50
	v_rcp_f32_e32 v51, v50
	v_add_f32_e32 v11, 1.0, v11
	v_rcp_f32_e32 v50, v11
	v_exp_f32_e32 v11, v56
	v_add_f32_e32 v52, 1.0, v52
	v_rcp_f32_e32 v53, v52
	v_exp_f32_e32 v54, v73
	v_add_f32_e32 v11, 1.0, v11
	v_rcp_f32_e32 v52, v11
	v_exp_f32_e32 v11, v57
	v_add_f32_e32 v54, 1.0, v54
	v_rcp_f32_e32 v55, v54
	v_exp_f32_e32 v56, v74
	v_add_f32_e32 v11, 1.0, v11
	v_rcp_f32_e32 v54, v11
	v_exp_f32_e32 v11, v58
	v_add_f32_e32 v56, 1.0, v56
	v_rcp_f32_e32 v57, v56
	v_exp_f32_e32 v58, v75
	v_add_f32_e32 v11, 1.0, v11
	v_rcp_f32_e32 v56, v11
	v_exp_f32_e32 v11, v59
	v_add_f32_e32 v58, 1.0, v58
	v_rcp_f32_e32 v59, v58
	v_exp_f32_e32 v64, v76
	v_add_f32_e32 v11, 1.0, v11
	v_rcp_f32_e32 v58, v11
	v_exp_f32_e32 v11, v60
	v_add_f32_e32 v60, 1.0, v64
	v_rcp_f32_e32 v65, v60
	v_exp_f32_e32 v60, v77
	v_add_f32_e32 v11, 1.0, v11
	v_rcp_f32_e32 v64, v11
	v_exp_f32_e32 v11, v61
	v_exp_f32_e32 v7, v66
	v_exp_f32_e32 v66, v78
	v_add_f32_e32 v60, 1.0, v60
	v_add_f32_e32 v11, 1.0, v11
	v_rcp_f32_e32 v61, v60
	v_rcp_f32_e32 v60, v11
	v_exp_f32_e32 v11, v62
	v_add_f32_e32 v62, 1.0, v66
	v_add_f32_e32 v7, 1.0, v7
	v_add_f32_e32 v6, 1.0, v6
	v_rcp_f32_e32 v67, v62
	v_exp_f32_e32 v62, v79
	v_rcp_f32_e32 v4, v4
	v_rcp_f32_e32 v7, v7
	v_rcp_f32_e32 v6, v6
	v_rcp_f32_e32 v8, v8
	v_exp_f32_e32 v68, v63
	v_add_f32_e32 v11, 1.0, v11
	v_rcp_f32_e32 v66, v11
	v_add_f32_e32 v11, 1.0, v62
	v_rcp_f32_e32 v63, v11
	v_add_f32_e32 v11, 1.0, v68
	v_pk_mul_f32 v[68:69], v[2:3], v[6:7]
	v_pk_mul_f32 v[70:71], v[4:5], v[8:9]
	v_pk_mul_f32 v[68:69], v[12:13], v[68:69]
	v_pk_mul_f32 v[70:71], v[14:15], v[70:71]
	v_rcp_f32_e32 v62, v11
	v_pk_mul_f32 v[68:69], v[48:49], v[68:69]
	v_pk_mul_f32 v[70:71], v[50:51], v[70:71]
	v_pk_mul_f32 v[68:69], v[52:53], v[68:69]
	v_pk_mul_f32 v[70:71], v[54:55], v[70:71]
	v_pk_mul_f32 v[68:69], v[56:57], v[68:69]
	v_pk_mul_f32 v[70:71], v[58:59], v[70:71]
	v_pk_mul_f32 v[68:69], v[64:65], v[68:69]
	v_pk_mul_f32 v[70:71], v[60:61], v[70:71]
	v_pk_mul_f32 v[68:69], v[66:67], v[68:69]
	v_pk_mul_f32 v[70:71], v[62:63], v[70:71]
	v_sub_f32_e32 v3, 1.0, v3
	v_pk_mul_f32 v[68:69], v[68:69], v[70:71]
	s_nop 0
	v_mul_f32_e32 v11, v68, v69
	ds_bpermute_b32 v68, v230, v11
	s_waitcnt lgkmcnt(0)
; #define LAS __attribute__((address_space(3)))
; __device__ __forceinline__ unsigned pk2(float lo, float hi) { return pg8::cvt_pk_bf16(lo, hi); }
; __device__ __forceinline__ void attn_tile_scores(AttnState& st, u32x4 (&pw)[4], const bf16x8 (&qf)[4], const bf16x8 (&kf)[2][4], int kv0, int P0, int pq, int hi) {
;     ...
;     float run = hi ? st.carry : st.carry * oth;
;     st.carry = st.carry * (tot * oth);
; #pragma unroll
;     for (int r = 15; r >= 0; --r) { s1[r] = (1.0f - k1v[r]) * run; run *= k1v[r]; }
; #pragma unroll
;     for (int r = 15; r >= 0; --r) { s0[r] = (1.0f - k0v[r]) * run; run *= k0v[r]; }
;     pw[0] = (u32x4){pk2(s0[0], s0[1]), pk2(s0[2], s0[3]), pk2(s0[4], s0[5]), pk2(s0[6], s0[7])};
;     pw[1] = (u32x4){pk2(s0[8], s0[9]), pk2(s0[10], s0[11]), pk2(s0[12], s0[13]), pk2(s0[14], s0[15])};
;     pw[2] = (u32x4){pk2(s1[0], s1[1]), pk2(s1[2], s1[3]), pk2(s1[4], s1[5]), pk2(s1[6], s1[7])};
;     pw[3] = (u32x4){pk2(s1[8], s1[9]), pk2(s1[10], s1[11]), pk2(s1[12], s1[13]), pk2(s1[14], s1[15])};
; }
; __device__ __forceinline__ bool attn_tile_pv(AttnState& st, const u32x4 (&pw)[4], const bf16x8 (&vf)[2][4]) {
; #pragma unroll
;     for (int c = 0; c < 4; ++c) { const bf16x8 pf = __builtin_bit_cast(bf16x8, pw[c]);
;         st.o0 = __builtin_amdgcn_mfma_f32_32x32x16_bf16(vf[0][c], pf, st.o0, 0, 0, 0); st.o1 = __builtin_amdgcn_mfma_f32_32x32x16_bf16(vf[1][c], pf, st.o1, 0, 0, 0); }
;     return __all(st.carry < 1.1754944e-38f) != 0;
; __device__ __forceinline__ void sb_attn_wave(LAS unsigned char* lds, int Tlo, const bf16* __restrict__ u, const bf16* __restrict__ um, const bf16* __restrict__ vT, const bf16* __restrict__ vTm, ...
;     ...
;         for (int dh = 0; dh < 2; ++dh)
; #pragma unroll
;             for (int c = 0; c < 4; ++c) vf[dh][c] = *(const LAS bf16x8*)(vbase + so + dh * 32 * AT_PITCH + c * 16);
;         done = attn_tile_pv(st, pw, vf);
	v_mul_f32_e32 v69, v211, v68
	v_cndmask_b32_e64 v69, v211, v69, s[38:39]
	v_mul_f32_e32 v11, v11, v68
	v_sub_f32_e32 v68, 1.0, v62
	v_mul_f32_e32 v68, v69, v68
	v_mul_f32_e32 v62, v62, v69
	v_sub_f32_e32 v69, 1.0, v66
	v_mul_f32_e32 v69, v69, v62
	v_mul_f32_e32 v62, v66, v62
	v_sub_f32_e32 v66, 1.0, v60
	v_mul_f32_e32 v66, v66, v62
	v_mul_f32_e32 v60, v60, v62
	v_sub_f32_e32 v62, 1.0, v64
	v_mul_f32_e32 v62, v62, v60
	v_mul_f32_e32 v60, v64, v60
	v_sub_f32_e32 v64, 1.0, v58
	v_mul_f32_e32 v64, v64, v60
	v_mul_f32_e32 v58, v58, v60
	v_sub_f32_e32 v60, 1.0, v56
	v_mul_f32_e32 v60, v60, v58
	v_mul_f32_e32 v56, v56, v58
	v_sub_f32_e32 v58, 1.0, v54
	v_mul_f32_e32 v58, v58, v56
	v_mul_f32_e32 v54, v54, v56
	v_sub_f32_e32 v56, 1.0, v52
	v_mul_f32_e32 v56, v56, v54
	v_mul_f32_e32 v52, v52, v54
	v_sub_f32_e32 v54, 1.0, v50
	v_mul_f32_e32 v54, v54, v52
	v_mul_f32_e32 v50, v50, v52
	v_sub_f32_e32 v52, 1.0, v48
	v_mul_f32_e32 v52, v52, v50
	v_mul_f32_e32 v48, v48, v50
	v_sub_f32_e32 v50, 1.0, v14
	v_mul_f32_e32 v50, v50, v48
	v_mul_f32_e32 v14, v14, v48
	v_sub_f32_e32 v48, 1.0, v12
	v_mul_f32_e32 v48, v48, v14
	v_mul_f32_e32 v12, v12, v14
	v_sub_f32_e32 v14, 1.0, v8
	v_mul_f32_e32 v14, v14, v12
	v_mul_f32_e32 v8, v8, v12
	v_sub_f32_e32 v12, 1.0, v6
	v_mul_f32_e32 v70, v12, v8
	v_mul_f32_e32 v6, v6, v8
	v_sub_f32_e32 v8, 1.0, v4
	v_mul_f32_e32 v12, v8, v6
	v_mul_f32_e32 v4, v4, v6
	v_sub_f32_e32 v6, 1.0, v2
	v_mul_f32_e32 v71, v6, v4
	v_mul_f32_e32 v2, v2, v4
	v_sub_f32_e32 v4, 1.0, v63
	v_mul_f32_e32 v72, v4, v2
	v_mul_f32_e32 v2, v63, v2
	v_sub_f32_e32 v4, 1.0, v67
	v_mul_f32_e32 v63, v4, v2
	v_mul_f32_e32 v2, v67, v2
	v_sub_f32_e32 v4, 1.0, v61
	v_mul_f32_e32 v8, v4, v2
	v_mul_f32_e32 v2, v61, v2
	v_sub_f32_e32 v4, 1.0, v65
	v_mul_f32_e32 v61, v4, v2
	v_mul_f32_e32 v2, v65, v2
	v_sub_f32_e32 v4, 1.0, v59
	v_mul_f32_e32 v65, v4, v2
	v_mul_f32_e32 v2, v59, v2
	v_sub_f32_e32 v4, 1.0, v57
	v_mul_f32_e32 v59, v4, v2
	v_mul_f32_e32 v2, v57, v2
	v_sub_f32_e32 v4, 1.0, v55
	v_mul_f32_e32 v6, v4, v2
	v_mul_f32_e32 v2, v55, v2
	v_sub_f32_e32 v4, 1.0, v53
	v_mul_f32_e32 v55, v4, v2
	v_mul_f32_e32 v2, v53, v2
	v_sub_f32_e32 v4, 1.0, v51
	v_mul_f32_e32 v53, v4, v2
	v_mul_f32_e32 v2, v51, v2
	v_sub_f32_e32 v4, 1.0, v49
	v_mul_f32_e32 v51, v4, v2
	v_mul_f32_e32 v2, v49, v2
	v_sub_f32_e32 v4, 1.0, v15
	v_mul_f32_e32 v4, v4, v2
	v_mul_f32_e32 v2, v15, v2
	v_sub_f32_e32 v15, 1.0, v13
	v_mul_f32_e32 v15, v15, v2
	v_mul_f32_e32 v2, v13, v2
	v_sub_f32_e32 v13, 1.0, v9
	v_mul_f32_e32 v13, v13, v2
	v_mul_f32_e32 v2, v9, v2
	v_sub_f32_e32 v9, 1.0, v7
	v_mul_f32_e32 v9, v9, v2
	v_mul_f32_e32 v2, v7, v2
	v_sub_f32_e32 v7, 1.0, v5
	v_mul_f32_e32 v7, v7, v2
	v_mul_f32_e32 v2, v5, v2
	v_mul_f32_e32 v2, v3, v2
	v_cvt_pk_bf16_f32 v2, v2, v7
	v_cvt_pk_bf16_f32 v3, v9, v13
	v_cvt_pk_bf16_f32 v4, v15, v4
	v_cvt_pk_bf16_f32 v5, v51, v53
	v_cvt_pk_bf16_f32 v6, v55, v6
	v_cvt_pk_bf16_f32 v7, v59, v65
	v_cvt_pk_bf16_f32 v8, v61, v8
	v_cvt_pk_bf16_f32 v9, v63, v72
	v_cvt_pk_bf16_f32 v12, v71, v12
	v_cvt_pk_bf16_f32 v13, v70, v14
	v_cvt_pk_bf16_f32 v14, v48, v50
	v_cvt_pk_bf16_f32 v15, v52, v54
	v_cvt_pk_bf16_f32 v48, v56, v58
	v_cvt_pk_bf16_f32 v49, v60, v64
	v_cvt_pk_bf16_f32 v50, v62, v66
	v_cvt_pk_bf16_f32 v51, v69, v68
	v_add_u32_e32 v56, v10, v209
	v_add_u32_e32 v57, 0x10e00, v56
	ds_read_b128 v[154:157], v56 offset:64512
	ds_read_b128 v[158:161], v57
	ds_read_b128 v[162:165], v56 offset:64528
	ds_read_b128 v[166:169], v57 offset:16
	ds_read_b128 v[218:221], v56 offset:64544
	ds_read_b128 v[222:225], v57 offset:32
	ds_read_b128 v[226:229], v56 offset:64560
	ds_read_b128 v[244:247], v57 offset:48
	v_mul_f32_e32 v211, v211, v11
	v_cmp_gt_f32_e32 vcc, s31, v211
	s_cmp_eq_u64 vcc, exec
	s_cselect_b64 s[48:49], -1, 0
	s_add_i32 s56, s58, -1
	s_cmp_le_i32 s58, s55
	s_cselect_b64 s[58:59], -1, 0
	s_or_b64 s[58:59], s[58:59], s[48:49]
	v_add_u32_e32 v0, 64, v0
	s_sub_i32 s41, s41, 64
	v_add_u32_e32 v10, 0xffffdc00, v10
	s_and_b64 vcc, exec, s[58:59]
	s_mov_b32 s58, s56
	s_waitcnt lgkmcnt(7)
	v_mfma_f32_32x32x16_bf16 v[32:47], v[154:157], v[2:5], v[32:47]
	s_waitcnt lgkmcnt(6)
	v_mfma_f32_32x32x16_bf16 v[16:31], v[158:161], v[2:5], v[16:31]
	s_waitcnt lgkmcnt(5)
	v_mfma_f32_32x32x16_bf16 v[32:47], v[162:165], v[6:9], v[32:47]
	s_waitcnt lgkmcnt(4)
	v_mfma_f32_32x32x16_bf16 v[16:31], v[166:169], v[6:9], v[16:31]
	s_waitcnt lgkmcnt(3)
	v_mfma_f32_32x32x16_bf16 v[32:47], v[218:221], v[12:15], v[32:47]
	s_waitcnt lgkmcnt(2)
	v_mfma_f32_32x32x16_bf16 v[16:31], v[222:225], v[12:15], v[16:31]
	s_waitcnt lgkmcnt(1)
	v_mfma_f32_32x32x16_bf16 v[32:47], v[226:229], v[48:51], v[32:47]
	s_waitcnt lgkmcnt(0)
	v_mfma_f32_32x32x16_bf16 v[16:31], v[244:247], v[48:51], v[16:31]
	s_cbranch_vccnz .LBB0_284
